# S5 pass 3: the two carry loads of each 64-row outer step are requested one step ahead instead of load-then-wait at the top of every step
# speedup vs baseline: 1.0024x; 1.0005x over previous
.LBB0_980:
	s_lshl_b32 s2, s35, 12
	s_add_i32 s36, s2, 0
	s_add_i32 s20, s36, s23
	s_lshl_b32 s2, s25, 1
	s_add_u32 s2, s30, s2
	v_mov_b32_e32 v16, s20
	s_movk_i32 s20, 0x110
	s_addc_u32 s3, s31, 0
	v_mad_u32_u24 v90, v65, s20, v16
	v_lshlrev_b32_e32 v16, 1, v65
	s_mulk_i32 s35, 0x1100
	v_lshlrev_b32_e32 v87, 2, v60
	v_lshlrev_b32_e32 v89, 6, v64
	v_lshl_add_u64 v[60:61], s[2:3], 0, v[16:17]
	s_mov_b32 s2, 0x5040100
	s_add_i32 s20, s35, 0
	v_lshl_add_u32 v88, v65, 2, s36
	v_perm_b32 v37, v47, v46, s2
	v_perm_b32 v36, v45, v44, s2
	v_perm_b32 v35, v43, v42, s2
	v_perm_b32 v34, v41, v40, s2
	v_perm_b32 v41, v69, v63, s2
	v_perm_b32 v40, v62, v53, s2
	v_perm_b32 v39, v52, v51, s2
	v_perm_b32 v38, v49, v48, s2
	v_perm_b32 v45, v82, v80, s2
	v_perm_b32 v44, v78, v77, s2
	v_perm_b32 v43, v75, v73, s2
	v_perm_b32 v42, v72, v70, s2
	v_perm_b32 v49, v86, v85, s2
	v_perm_b32 v48, v84, v83, s2
	v_perm_b32 v47, v81, v79, s2
	v_perm_b32 v46, v76, v74, s2
	s_add_i32 s20, s20, 0xc000
	s_mov_b32 s21, 0
	v_add_u32_e32 v16, s36, v89
	v_add_u32_e32 v69, v90, v50
	s_waitcnt lgkmcnt(0)
	s_barrier
	v_mov_b32_e32 v132, s24
	v_add3_u32 v132, v132, s23, v65
	v_ashrrev_i32_e32 v133, 31, v132
	v_lshlrev_b64 v[132:133], 10, v[132:133]
	v_lshl_add_u64 v[130:131], v[58:59], 0, v[132:133]
	v_mov_b32_e32 v134, 0
	v_mov_b32_e32 v135, 0
	v_mov_b32_e32 v136, 0
	v_mov_b32_e32 v137, 0
	v_add_u32_e32 v154, s22, v67
	v_add_u32_e32 v154, 0x15800, v154
	v_add_u32_e32 v155, s20, v67
	s_and_saveexec_b64 s[2:3], s[4:5]
	global_load_dwordx4 v[134:137], v[130:131], off
	s_or_b64 exec, exec, s[2:3]
	v_add_co_u32_e32 v130, vcc, 0x4000, v130
	s_nop 1
	v_addc_co_u32_e32 v131, vcc, 0, v131, vcc
	s_add_i32 s100, s23, s24
	v_or_b32_e32 v184, s100, v64
	v_ashrrev_i32_e32 v185, 31, v184
	v_lshlrev_b64 v[184:185], 10, v[184:185]
	v_lshl_add_u64 v[184:185], s[0:1], 0, v[184:185]
	global_load_dwordx4 v[176:179], v[184:185], off offset:16
	global_load_dwordx4 v[180:183], v[184:185], off
	s_waitcnt vmcnt(0)
.LBB0_981:
	s_lshl_b32 s2, s21, 6
	s_add_i32 s2, s2, s23
	s_add_i32 s25, s2, s24
	s_waitcnt vmcnt(5)
	v_mov_b32_e32 v50, v176
	v_mov_b32_e32 v51, v177
	v_mov_b32_e32 v52, v178
	v_mov_b32_e32 v53, v179
	v_mov_b32_e32 v72, v180
	v_mov_b32_e32 v73, v181
	v_mov_b32_e32 v74, v182
	v_mov_b32_e32 v75, v183
	s_add_i32 s100, s21, 1
	s_min_u32 s100, s100, 3
	s_lshl_b32 s100, s100, 6
	s_add_i32 s100, s100, s23
	s_add_i32 s100, s100, s24
	v_or_b32_e32 v184, s100, v64
	v_ashrrev_i32_e32 v185, 31, v184
	v_lshlrev_b64 v[184:185], 10, v[184:185]
	v_lshl_add_u64 v[184:185], s[0:1], 0, v[184:185]
	global_load_dwordx4 v[176:179], v[184:185], off offset:16
	global_load_dwordx4 v[180:183], v[184:185], off
	v_or_b32_e32 v70, s25, v65
	s_mov_b32 s35, 0
	v_lshlrev_b32_e32 v80, 16, v50
	v_lshlrev_b32_e32 v76, 16, v72
	v_and_b32_e32 v77, 0xffff0000, v72
	v_lshlrev_b32_e32 v78, 16, v73
	v_and_b32_e32 v79, 0xffff0000, v73
	v_and_b32_e32 v81, 0xffff0000, v50
	v_lshlrev_b32_e32 v50, 16, v52
	v_lshlrev_b32_e32 v72, 16, v74
	v_and_b32_e32 v73, 0xffff0000, v74
	v_lshlrev_b32_e32 v74, 16, v75
	v_and_b32_e32 v75, 0xffff0000, v75
	v_lshlrev_b32_e32 v82, 16, v51
	v_and_b32_e32 v83, 0xffff0000, v51
	v_and_b32_e32 v51, 0xffff0000, v52
	v_lshlrev_b32_e32 v52, 16, v53
	v_and_b32_e32 v53, 0xffff0000, v53
	ds_write_b128 v16, v[76:79] offset:16384
	ds_write_b128 v16, v[72:75] offset:16400
	ds_write_b128 v16, v[80:83] offset:16416
	ds_write_b128 v16, v[50:53] offset:16432
	v_or_b32_e32 v50, s2, v64
	v_lshl_add_u32 v50, v50, 3, 0
	ds_read_b64 v[62:63], v50
